# conv_act: next-next row prefetched one iteration ahead (distance-1 software pipeline)
# speedup vs baseline: 1.0079x; 1.0079x over previous
.LBB0_1112:
	s_or_b64 exec, exec, s[40:41]
	s_movk_i32 s19, 0x1000
	v_add_co_u32_e32 v2, vcc, s19, v68
	v_and_b32_e32 v1, 0xffffefe0, v79
	s_nop 0
	v_addc_co_u32_e32 v3, vcc, 0, v69, vcc
	v_add_co_u32_e32 v122, vcc, 0x2c00, v68
	s_nop 1
	v_addc_co_u32_e32 v123, vcc, 0, v69, vcc
	v_add_co_u32_e32 v124, vcc, 0x2c00, v2
	s_nop 1
	v_addc_co_u32_e32 v125, vcc, 0, v3, vcc
	global_load_dwordx4 v[68:71], v[68:69], off nt
	s_nop 0
	global_load_dwordx4 v[72:75], v[2:3], off offset:1536 nt
	global_load_dwordx4 v[114:117], v[122:123], off nt
	global_load_dwordx4 v[118:121], v[124:125], off offset:1536 nt
	s_movk_i32 s19, 0xe0
	v_mad_i64_i32 v[2:3], s[20:21], v78, s16, 0
	s_waitcnt vmcnt(0)
	v_mov_b32_e32 v79, v6
	v_mov_b32_e32 v6, v10
	v_cmp_eq_u32_e32 vcc, s19, v1
	v_lshlrev_b64 v[76:77], 1, v[76:77]
	s_movk_i32 s19, 0x1600
	v_mov_b32_e32 v80, v14
	v_mov_b32_e32 v14, v18
	v_mov_b32_e32 v81, v22
	v_mov_b32_e32 v22, v26
	v_mov_b32_e32 v82, v30
	v_mov_b32_e32 v30, v34
	v_mov_b32_e32 v83, v38
	v_mov_b32_e32 v38, v42
	v_mov_b32_e32 v94, v46
	v_mov_b32_e32 v46, v50
	v_mov_b32_e32 v95, v54
	v_mov_b32_e32 v54, v58
	v_mov_b32_e32 v96, v62
	v_mov_b32_e32 v62, v66
	v_mov_b32_e32 v10, v9
	v_mov_b32_e32 v9, v6
	v_mov_b32_e32 v6, v5
	v_mov_b32_e32 v5, v79
	v_mad_i64_i32 v[78:79], s[20:21], v78, s19, v[76:77]
	v_lshl_add_u64 v[2:3], v[2:3], 0, v[76:77]
	v_swap_b32 v66, v65
	v_mov_b32_e32 v34, v33
	v_mov_b32_e32 v18, v17
	v_mov_b32_e32 v50, v49
	v_mov_b32_e32 v58, v57
	v_mov_b32_e32 v26, v25
	v_mov_b32_e32 v42, v41
	v_mov_b32_e32 v33, v30
	v_mov_b32_e32 v17, v14
	v_mov_b32_e32 v49, v46
	v_mov_b32_e32 v57, v54
	v_mov_b32_e32 v25, v22
	v_mov_b32_e32 v41, v38
	v_mov_b32_e32 v62, v61
	v_mov_b32_e32 v30, v29
	v_mov_b32_e32 v14, v13
	v_mov_b32_e32 v46, v45
	v_mov_b32_e32 v54, v53
	v_mov_b32_e32 v22, v21
	v_mov_b32_e32 v38, v37
	v_mov_b32_e32 v61, v96
	v_mov_b32_e32 v29, v82
	v_mov_b32_e32 v13, v80
	v_mov_b32_e32 v45, v94
	v_mov_b32_e32 v53, v95
	v_mov_b32_e32 v21, v81
	v_mov_b32_e32 v37, v83
	v_lshl_add_u64 v[94:95], s[52:53], 0, v[78:79]
	v_lshl_add_u64 v[96:97], s[74:75], 0, v[2:3]
	s_mov_b64 s[40:41], 0
	s_xor_b64 s[42:43], vcc, -1
	s_branch .LBB0_1114
.LBB0_1113:
	s_or_b64 exec, exec, s[44:45]
	v_lshlrev_b32_e32 v109, 16, v89
	v_lshlrev_b32_e32 v108, 16, v88
	v_lshlrev_b32_e32 v111, 16, v77
	v_lshlrev_b32_e32 v110, 16, v76
	v_and_b32_e32 v89, 0xffff0000, v89
	v_and_b32_e32 v88, 0xffff0000, v88
	v_pk_mul_f32 v[108:109], v[8:9], v[108:109]
	s_nop 0
	v_lshlrev_b32_e32 v2, 16, v68
	v_lshlrev_b32_e32 v3, 16, v69
	v_and_b32_e32 v113, 0xffff0000, v77
	v_and_b32_e32 v112, 0xffff0000, v76
	v_pk_fma_f32 v[108:109], v[24:25], v[110:111], v[108:109]
	v_pk_mul_f32 v[88:89], v[10:11], v[88:89]
	v_and_b32_e32 v100, 0xffff0000, v68
	v_and_b32_e32 v101, 0xffff0000, v69
	v_pk_fma_f32 v[2:3], v[40:41], v[2:3], v[108:109]
	v_pk_fma_f32 v[88:89], v[26:27], v[112:113], v[88:89]
	v_pk_add_f32 v[2:3], v[56:57], v[2:3]
	v_pk_fma_f32 v[88:89], v[42:43], v[100:101], v[88:89]
	v_mul_f32_e32 v1, 0xbfb8aa3b, v2
	v_pk_add_f32 v[88:89], v[58:59], v[88:89]
	v_exp_f32_e32 v108, v1
	v_mul_f32_e32 v1, 0xbfb8aa3b, v88
	v_exp_f32_e32 v100, v1
	v_mul_f32_e32 v1, 0xbfb8aa3b, v3
	v_lshlrev_b32_e32 v102, 16, v84
	v_lshlrev_b32_e32 v103, 16, v85
	v_exp_f32_e32 v109, v1
	v_lshlrev_b32_e32 v104, 16, v80
	v_and_b32_e32 v84, 0xffff0000, v84
	v_lshlrev_b32_e32 v105, 16, v81
	v_and_b32_e32 v85, 0xffff0000, v85
	v_pk_mul_f32 v[102:103], v[16:17], v[102:103]
	v_and_b32_e32 v106, 0xffff0000, v80
	v_and_b32_e32 v107, 0xffff0000, v81
	v_pk_fma_f32 v[102:103], v[32:33], v[104:105], v[102:103]
	s_nop 0
	v_lshlrev_b32_e32 v105, 16, v73
	v_lshlrev_b32_e32 v104, 16, v72
	v_pk_mul_f32 v[84:85], v[18:19], v[84:85]
	v_pk_fma_f32 v[102:103], v[48:49], v[104:105], v[102:103]
	v_pk_fma_f32 v[84:85], v[34:35], v[106:107], v[84:85]
	v_and_b32_e32 v105, 0xffff0000, v73
	v_and_b32_e32 v104, 0xffff0000, v72
	v_pk_fma_f32 v[84:85], v[50:51], v[104:105], v[84:85]
	v_pk_add_f32 v[104:105], v[108:109], 1.0 op_sel_hi:[1,0]
	v_pk_add_f32 v[102:103], v[64:65], v[102:103]
	v_div_scale_f32 v1, s[20:21], v105, v105, v3
	v_rcp_f32_e32 v99, v1
	v_lshlrev_b32_e32 v109, 16, v91
	v_lshlrev_b32_e32 v108, 16, v90
	v_pk_add_f32 v[84:85], v[66:67], v[84:85]
	v_fma_f32 v101, -v1, v99, 1.0
	v_fmac_f32_e32 v99, v101, v99
	v_div_scale_f32 v101, vcc, v3, v105, v3
	v_mul_f32_e32 v106, v101, v99
	v_fma_f32 v107, -v1, v106, v101
	v_fmac_f32_e32 v106, v107, v99
	v_fma_f32 v1, -v1, v106, v101
	v_div_fmas_f32 v1, v1, v99, v106
	v_div_fixup_f32 v3, v1, v105, v3
	v_div_scale_f32 v1, s[20:21], v104, v104, v2
	v_rcp_f32_e32 v99, v1
	v_lshlrev_b32_e32 v111, 16, v79
	v_lshlrev_b32_e32 v110, 16, v78
	v_and_b32_e32 v91, 0xffff0000, v91
	v_fma_f32 v101, -v1, v99, 1.0
	v_fmac_f32_e32 v99, v101, v99
	v_div_scale_f32 v101, vcc, v2, v104, v2
	v_mul_f32_e32 v105, v101, v99
	v_fma_f32 v106, -v1, v105, v101
	v_fmac_f32_e32 v105, v106, v99
	v_fma_f32 v1, -v1, v105, v101
	v_div_fmas_f32 v1, v1, v99, v105
	v_div_fixup_f32 v2, v1, v104, v2
	v_mul_f32_e32 v1, 0xbfb8aa3b, v89
	v_exp_f32_e32 v101, v1
	v_pk_mul_f32 v[2:3], v[102:103], v[2:3]
	v_and_b32_e32 v90, 0xffff0000, v90
	v_pk_mul_f32 v[108:109], v[4:5], v[108:109]
	v_pk_add_f32 v[100:101], v[100:101], 1.0 op_sel_hi:[1,0]
	v_and_b32_e32 v113, 0xffff0000, v79
	v_div_scale_f32 v1, s[20:21], v101, v101, v89
	v_rcp_f32_e32 v99, v1
	v_and_b32_e32 v112, 0xffff0000, v78
	v_pk_fma_f32 v[108:109], v[20:21], v[110:111], v[108:109]
	v_pk_mul_f32 v[90:91], v[6:7], v[90:91]
	v_fma_f32 v102, -v1, v99, 1.0
	v_fmac_f32_e32 v99, v102, v99
	v_div_scale_f32 v102, vcc, v89, v101, v89
	v_mul_f32_e32 v103, v102, v99
	v_fma_f32 v104, -v1, v103, v102
	v_fmac_f32_e32 v103, v104, v99
	v_fma_f32 v1, -v1, v103, v102
	v_div_fmas_f32 v1, v1, v99, v103
	v_div_fixup_f32 v89, v1, v101, v89
	v_div_scale_f32 v1, s[20:21], v100, v100, v88
	v_rcp_f32_e32 v99, v1
	v_pk_fma_f32 v[90:91], v[22:23], v[112:113], v[90:91]
	v_lshlrev_b32_e32 v104, 16, v82
	v_lshlrev_b32_e32 v105, 16, v83
	v_fma_f32 v101, -v1, v99, 1.0
	v_fmac_f32_e32 v99, v101, v99
	v_div_scale_f32 v101, vcc, v88, v100, v88
	v_mul_f32_e32 v102, v101, v99
	v_fma_f32 v103, -v1, v102, v101
	v_fmac_f32_e32 v102, v103, v99
	v_fma_f32 v1, -v1, v102, v101
	v_div_fmas_f32 v1, v1, v99, v102
	v_div_fixup_f32 v88, v1, v100, v88
	v_pk_mul_f32 v[84:85], v[84:85], v[88:89]
	v_lshlrev_b32_e32 v88, 16, v70
	v_lshlrev_b32_e32 v89, 16, v71
	v_and_b32_e32 v100, 0xffff0000, v70
	v_and_b32_e32 v101, 0xffff0000, v71
	v_pk_fma_f32 v[88:89], v[36:37], v[88:89], v[108:109]
	v_pk_fma_f32 v[90:91], v[38:39], v[100:101], v[90:91]
	v_pk_add_f32 v[88:89], v[52:53], v[88:89]
	v_pk_add_f32 v[90:91], v[54:55], v[90:91]
	v_mul_f32_e32 v1, 0xbfb8aa3b, v88
	v_exp_f32_e32 v108, v1
	v_mul_f32_e32 v1, 0xbfb8aa3b, v90
	v_exp_f32_e32 v100, v1
	v_mul_f32_e32 v1, 0xbfb8aa3b, v89
	v_lshlrev_b32_e32 v102, 16, v86
	v_lshlrev_b32_e32 v103, 16, v87
	v_exp_f32_e32 v109, v1
	v_and_b32_e32 v86, 0xffff0000, v86
	v_and_b32_e32 v87, 0xffff0000, v87
	v_pk_mul_f32 v[102:103], v[12:13], v[102:103]
	v_and_b32_e32 v106, 0xffff0000, v82
	v_and_b32_e32 v107, 0xffff0000, v83
	v_pk_fma_f32 v[102:103], v[28:29], v[104:105], v[102:103]
	v_lshlrev_b32_e32 v105, 16, v75
	v_lshlrev_b32_e32 v104, 16, v74
	v_pk_mul_f32 v[86:87], v[14:15], v[86:87]
	v_pk_fma_f32 v[102:103], v[44:45], v[104:105], v[102:103]
	v_pk_fma_f32 v[86:87], v[30:31], v[106:107], v[86:87]
	v_and_b32_e32 v105, 0xffff0000, v75
	v_and_b32_e32 v104, 0xffff0000, v74
	v_pk_fma_f32 v[86:87], v[46:47], v[104:105], v[86:87]
	v_pk_add_f32 v[104:105], v[108:109], 1.0 op_sel_hi:[1,0]
	v_pk_add_f32 v[102:103], v[60:61], v[102:103]
	v_div_scale_f32 v1, s[20:21], v105, v105, v89
	v_rcp_f32_e32 v99, v1
	v_pk_add_f32 v[86:87], v[62:63], v[86:87]
	s_add_u32 s40, s40, 0x2c00
	s_addc_u32 s41, s41, 0
	v_fma_f32 v101, -v1, v99, 1.0
	v_fmac_f32_e32 v99, v101, v99
	v_div_scale_f32 v101, vcc, v89, v105, v89
	v_mul_f32_e32 v106, v101, v99
	v_fma_f32 v107, -v1, v106, v101
	v_fmac_f32_e32 v106, v107, v99
	v_fma_f32 v1, -v1, v106, v101
	v_div_fmas_f32 v1, v1, v99, v106
	v_div_fixup_f32 v89, v1, v105, v89
	v_div_scale_f32 v1, s[20:21], v104, v104, v88
	v_rcp_f32_e32 v99, v1
	s_cmp_eq_u32 s40, 0x58000
	v_fma_f32 v101, -v1, v99, 1.0
	v_fmac_f32_e32 v99, v101, v99
	v_div_scale_f32 v101, vcc, v88, v104, v88
	v_mul_f32_e32 v105, v101, v99
	v_fma_f32 v106, -v1, v105, v101
	v_fmac_f32_e32 v105, v106, v99
	v_fma_f32 v1, -v1, v105, v101
	v_div_fmas_f32 v1, v1, v99, v105
	v_div_fixup_f32 v88, v1, v104, v88
	v_mul_f32_e32 v1, 0xbfb8aa3b, v91
	v_exp_f32_e32 v101, v1
	v_pk_mul_f32 v[88:89], v[102:103], v[88:89]
	v_pk_add_f32 v[100:101], v[100:101], 1.0 op_sel_hi:[1,0]
	s_nop 0
	v_div_scale_f32 v1, s[20:21], v101, v101, v91
	v_rcp_f32_e32 v99, v1
	s_nop 0
	v_fma_f32 v102, -v1, v99, 1.0
	v_fmac_f32_e32 v99, v102, v99
	v_div_scale_f32 v102, vcc, v91, v101, v91
	v_mul_f32_e32 v103, v102, v99
	v_fma_f32 v104, -v1, v103, v102
	v_fmac_f32_e32 v103, v104, v99
	v_fma_f32 v1, -v1, v103, v102
	v_div_fmas_f32 v1, v1, v99, v103
	v_div_fixup_f32 v91, v1, v101, v91
	v_div_scale_f32 v1, s[20:21], v100, v100, v90
	v_rcp_f32_e32 v99, v1
	s_mov_b64 s[20:21], 0x1600
	v_fma_f32 v101, -v1, v99, 1.0
	v_fmac_f32_e32 v99, v101, v99
	v_div_scale_f32 v101, vcc, v90, v100, v90
	v_mul_f32_e32 v102, v101, v99
	v_fma_f32 v103, -v1, v102, v101
	v_fmac_f32_e32 v102, v103, v99
	v_fma_f32 v1, -v1, v102, v101
	v_div_fmas_f32 v1, v1, v99, v102
	v_div_fixup_f32 v90, v1, v100, v90
	v_pk_mul_f32 v[86:87], v[86:87], v[90:91]
	v_bfe_u32 v91, v85, 16, 1
	v_bfe_u32 v1, v87, 16, 1
	v_bfe_u32 v90, v86, 16, 1
	v_bfe_u32 v99, v84, 16, 1
	v_add3_u32 v84, v84, v99, s18
	v_add3_u32 v85, v85, v91, s18
	v_add3_u32 v86, v86, v90, s18
	v_add3_u32 v1, v87, v1, s18
	v_bfe_u32 v87, v2, 16, 1
	v_bfe_u32 v90, v3, 16, 1
	v_bfe_u32 v91, v88, 16, 1
	v_bfe_u32 v99, v89, 16, 1
	v_add3_u32 v89, v89, v99, s18
	v_add3_u32 v88, v88, v91, s18
	v_add3_u32 v3, v3, v90, s18
	v_add3_u32 v2, v2, v87, s18
	v_lshrrev_b32_e32 v2, 16, v2
	v_lshrrev_b32_e32 v3, 16, v3
	v_lshrrev_b32_e32 v88, 16, v88
	v_lshrrev_b32_e32 v87, 16, v89
	v_and_or_b32 v87, v1, s17, v87
	v_and_or_b32 v86, v86, s17, v88
	v_and_or_b32 v85, v85, s17, v3
	v_and_or_b32 v84, v84, s17, v2
	global_store_dwordx4 v[94:95], v[84:87], off
	v_mov_b64_e32 v[90:91], v[78:79]
	v_lshl_add_u64 v[94:95], v[94:95], 0, s[20:21]
	v_mov_b64_e32 v[86:87], v[82:83]
	v_mov_b64_e32 v[84:85], v[80:81]
	v_mov_b64_e32 v[88:89], v[76:77]
	s_cbranch_scc1 .LBB0_1109
.LBB0_1114:
	v_mov_b64_e32 v[78:79], v[70:71]
	v_mov_b64_e32 v[82:83], v[74:75]
	s_cmp_lg_u32 s40, 0x55400
	v_mov_b32_e32 v2, v0
	v_mov_b32_e32 v3, v0
	v_mov_b64_e32 v[76:77], v[68:69]
	v_mov_b64_e32 v[80:81], v[72:73]
	s_cselect_b64 s[20:21], -1, 0
	v_mov_b32_e32 v1, v0
	v_mov_b64_e32 v[70:71], v[2:3]
	v_mov_b64_e32 v[74:75], v[2:3]
	s_or_b64 s[20:21], s[42:43], s[20:21]
	v_mov_b64_e32 v[68:69], v[0:1]
	v_mov_b64_e32 v[72:73], v[0:1]
	s_and_saveexec_b64 s[44:45], s[20:21]
	s_cbranch_execz .LBB0_1113
	s_waitcnt vmcnt(1)
	v_mov_b64_e32 v[68:69], v[114:115]
	v_mov_b64_e32 v[70:71], v[116:117]
	v_mov_b64_e32 v[72:73], v[118:119]
	v_mov_b64_e32 v[74:75], v[120:121]
	s_cmp_lg_u32 s40, 0x52800
	s_cselect_b64 vcc, -1, 0
	s_or_b64 vcc, s[42:43], vcc
	s_cmp_lg_u32 s40, 0x55400
	s_cselect_b64 s[20:21], -1, 0
	s_and_b64 vcc, vcc, s[20:21]
	s_and_b64 exec, exec, vcc
	s_cbranch_execz .LBB0_1113
	v_lshl_add_u64 v[2:3], v[96:97], 0, s[40:41]
	v_add_co_u32_e32 v122, vcc, 0x6d54c00, v2
	s_nop 1
	v_addc_co_u32_e32 v123, vcc, 0, v3, vcc
	v_add_co_u32_e32 v2, vcc, 0x6d56c00, v2
	s_nop 1
	v_addc_co_u32_e32 v3, vcc, 0, v3, vcc
	global_load_dwordx4 v[114:117], v[122:123], off offset:3072 nt
	global_load_dwordx4 v[118:121], v[2:3], off offset:512 nt
	s_branch .LBB0_1113

.LBB0_1248:
	s_or_b64 exec, exec, s[42:43]
	s_movk_i32 s19, 0x1000
	v_add_co_u32_e32 v2, vcc, s19, v68
	v_and_b32_e32 v1, 0xffffefe0, v79
	s_nop 0
	v_addc_co_u32_e32 v3, vcc, 0, v69, vcc
	v_add_co_u32_e32 v122, vcc, 0x2c00, v68
	s_nop 1
	v_addc_co_u32_e32 v123, vcc, 0, v69, vcc
	v_add_co_u32_e32 v124, vcc, 0x2c00, v2
	s_nop 1
	v_addc_co_u32_e32 v125, vcc, 0, v3, vcc
	global_load_dwordx4 v[68:71], v[68:69], off nt
	s_nop 0
	global_load_dwordx4 v[72:75], v[2:3], off offset:1536 nt
	global_load_dwordx4 v[114:117], v[122:123], off nt
	global_load_dwordx4 v[118:121], v[124:125], off offset:1536 nt
	s_movk_i32 s19, 0xe0
	v_mad_i64_i32 v[2:3], s[20:21], v78, s16, 0
	s_waitcnt vmcnt(0)
	v_mov_b32_e32 v79, v6
	v_mov_b32_e32 v6, v10
	v_cmp_eq_u32_e32 vcc, s19, v1
	v_lshlrev_b64 v[76:77], 1, v[76:77]
	s_movk_i32 s19, 0x1600
	v_mov_b32_e32 v80, v14
	v_mov_b32_e32 v14, v18
	v_mov_b32_e32 v81, v22
	v_mov_b32_e32 v22, v26
	v_mov_b32_e32 v82, v30
	v_mov_b32_e32 v30, v34
	v_mov_b32_e32 v83, v38
	v_mov_b32_e32 v38, v42
	v_mov_b32_e32 v94, v46
	v_mov_b32_e32 v46, v50
	v_mov_b32_e32 v95, v54
	v_mov_b32_e32 v54, v58
	v_mov_b32_e32 v96, v62
	v_mov_b32_e32 v62, v66
	v_mov_b32_e32 v10, v9
	v_mov_b32_e32 v9, v6
	v_mov_b32_e32 v6, v5
	v_mov_b32_e32 v5, v79
	v_mad_i64_i32 v[78:79], s[20:21], v78, s19, v[76:77]
	v_lshl_add_u64 v[2:3], v[2:3], 0, v[76:77]
	v_swap_b32 v66, v65
	v_mov_b32_e32 v34, v33
	v_mov_b32_e32 v18, v17
	v_mov_b32_e32 v50, v49
	v_mov_b32_e32 v58, v57
	v_mov_b32_e32 v26, v25
	v_mov_b32_e32 v42, v41
	v_mov_b32_e32 v33, v30
	v_mov_b32_e32 v17, v14
	v_mov_b32_e32 v49, v46
	v_mov_b32_e32 v57, v54
	v_mov_b32_e32 v25, v22
	v_mov_b32_e32 v41, v38
	v_mov_b32_e32 v62, v61
	v_mov_b32_e32 v30, v29
	v_mov_b32_e32 v14, v13
	v_mov_b32_e32 v46, v45
	v_mov_b32_e32 v54, v53
	v_mov_b32_e32 v22, v21
	v_mov_b32_e32 v38, v37
	v_mov_b32_e32 v61, v96
	v_mov_b32_e32 v29, v82
	v_mov_b32_e32 v13, v80
	v_mov_b32_e32 v45, v94
	v_mov_b32_e32 v53, v95
	v_mov_b32_e32 v21, v81
	v_mov_b32_e32 v37, v83
	v_lshl_add_u64 v[94:95], s[38:39], 0, v[78:79]
	v_lshl_add_u64 v[96:97], s[74:75], 0, v[2:3]
	s_mov_b64 s[42:43], 0
	s_xor_b64 s[44:45], vcc, -1
	s_branch .LBB0_1250
.LBB0_1249:
	s_or_b64 exec, exec, s[46:47]
	v_lshlrev_b32_e32 v109, 16, v89
	v_lshlrev_b32_e32 v108, 16, v88
	v_lshlrev_b32_e32 v111, 16, v77
	v_lshlrev_b32_e32 v110, 16, v76
	v_and_b32_e32 v89, 0xffff0000, v89
	v_and_b32_e32 v88, 0xffff0000, v88
	v_pk_mul_f32 v[108:109], v[8:9], v[108:109]
	s_nop 0
	v_lshlrev_b32_e32 v2, 16, v68
	v_lshlrev_b32_e32 v3, 16, v69
	v_and_b32_e32 v113, 0xffff0000, v77
	v_and_b32_e32 v112, 0xffff0000, v76
	v_pk_fma_f32 v[108:109], v[24:25], v[110:111], v[108:109]
	v_pk_mul_f32 v[88:89], v[10:11], v[88:89]
	v_and_b32_e32 v100, 0xffff0000, v68
	v_and_b32_e32 v101, 0xffff0000, v69
	v_pk_fma_f32 v[2:3], v[40:41], v[2:3], v[108:109]
	v_pk_fma_f32 v[88:89], v[26:27], v[112:113], v[88:89]
	v_pk_add_f32 v[2:3], v[56:57], v[2:3]
	v_pk_fma_f32 v[88:89], v[42:43], v[100:101], v[88:89]
	v_mul_f32_e32 v1, 0xbfb8aa3b, v2
	v_pk_add_f32 v[88:89], v[58:59], v[88:89]
	v_exp_f32_e32 v108, v1
	v_mul_f32_e32 v1, 0xbfb8aa3b, v88
	v_exp_f32_e32 v100, v1
	v_mul_f32_e32 v1, 0xbfb8aa3b, v3
	v_lshlrev_b32_e32 v102, 16, v84
	v_lshlrev_b32_e32 v103, 16, v85
	v_exp_f32_e32 v109, v1
	v_lshlrev_b32_e32 v104, 16, v80
	v_and_b32_e32 v84, 0xffff0000, v84
	v_lshlrev_b32_e32 v105, 16, v81
	v_and_b32_e32 v85, 0xffff0000, v85
	v_pk_mul_f32 v[102:103], v[16:17], v[102:103]
	v_and_b32_e32 v106, 0xffff0000, v80
	v_and_b32_e32 v107, 0xffff0000, v81
	v_pk_fma_f32 v[102:103], v[32:33], v[104:105], v[102:103]
	s_nop 0
	v_lshlrev_b32_e32 v105, 16, v73
	v_lshlrev_b32_e32 v104, 16, v72
	v_pk_mul_f32 v[84:85], v[18:19], v[84:85]
	v_pk_fma_f32 v[102:103], v[48:49], v[104:105], v[102:103]
	v_pk_fma_f32 v[84:85], v[34:35], v[106:107], v[84:85]
	v_and_b32_e32 v105, 0xffff0000, v73
	v_and_b32_e32 v104, 0xffff0000, v72
	v_pk_fma_f32 v[84:85], v[50:51], v[104:105], v[84:85]
	v_pk_add_f32 v[104:105], v[108:109], 1.0 op_sel_hi:[1,0]
	v_pk_add_f32 v[102:103], v[64:65], v[102:103]
	v_div_scale_f32 v1, s[20:21], v105, v105, v3
	v_rcp_f32_e32 v99, v1
	v_lshlrev_b32_e32 v109, 16, v91
	v_lshlrev_b32_e32 v108, 16, v90
	v_pk_add_f32 v[84:85], v[66:67], v[84:85]
	v_fma_f32 v101, -v1, v99, 1.0
	v_fmac_f32_e32 v99, v101, v99
	v_div_scale_f32 v101, vcc, v3, v105, v3
	v_mul_f32_e32 v106, v101, v99
	v_fma_f32 v107, -v1, v106, v101
	v_fmac_f32_e32 v106, v107, v99
	v_fma_f32 v1, -v1, v106, v101
	v_div_fmas_f32 v1, v1, v99, v106
	v_div_fixup_f32 v3, v1, v105, v3
	v_div_scale_f32 v1, s[20:21], v104, v104, v2
	v_rcp_f32_e32 v99, v1
	v_lshlrev_b32_e32 v111, 16, v79
	v_lshlrev_b32_e32 v110, 16, v78
	v_and_b32_e32 v91, 0xffff0000, v91
	v_fma_f32 v101, -v1, v99, 1.0
	v_fmac_f32_e32 v99, v101, v99
	v_div_scale_f32 v101, vcc, v2, v104, v2
	v_mul_f32_e32 v105, v101, v99
	v_fma_f32 v106, -v1, v105, v101
	v_fmac_f32_e32 v105, v106, v99
	v_fma_f32 v1, -v1, v105, v101
	v_div_fmas_f32 v1, v1, v99, v105
	v_div_fixup_f32 v2, v1, v104, v2
	v_mul_f32_e32 v1, 0xbfb8aa3b, v89
	v_exp_f32_e32 v101, v1
	v_pk_mul_f32 v[2:3], v[102:103], v[2:3]
	v_and_b32_e32 v90, 0xffff0000, v90
	v_pk_mul_f32 v[108:109], v[4:5], v[108:109]
	v_pk_add_f32 v[100:101], v[100:101], 1.0 op_sel_hi:[1,0]
	v_and_b32_e32 v113, 0xffff0000, v79
	v_div_scale_f32 v1, s[20:21], v101, v101, v89
	v_rcp_f32_e32 v99, v1
	v_and_b32_e32 v112, 0xffff0000, v78
	v_pk_fma_f32 v[108:109], v[20:21], v[110:111], v[108:109]
	v_pk_mul_f32 v[90:91], v[6:7], v[90:91]
	v_fma_f32 v102, -v1, v99, 1.0
	v_fmac_f32_e32 v99, v102, v99
	v_div_scale_f32 v102, vcc, v89, v101, v89
	v_mul_f32_e32 v103, v102, v99
	v_fma_f32 v104, -v1, v103, v102
	v_fmac_f32_e32 v103, v104, v99
	v_fma_f32 v1, -v1, v103, v102
	v_div_fmas_f32 v1, v1, v99, v103
	v_div_fixup_f32 v89, v1, v101, v89
	v_div_scale_f32 v1, s[20:21], v100, v100, v88
	v_rcp_f32_e32 v99, v1
	v_pk_fma_f32 v[90:91], v[22:23], v[112:113], v[90:91]
	v_lshlrev_b32_e32 v104, 16, v82
	v_lshlrev_b32_e32 v105, 16, v83
	v_fma_f32 v101, -v1, v99, 1.0
	v_fmac_f32_e32 v99, v101, v99
	v_div_scale_f32 v101, vcc, v88, v100, v88
	v_mul_f32_e32 v102, v101, v99
	v_fma_f32 v103, -v1, v102, v101
	v_fmac_f32_e32 v102, v103, v99
	v_fma_f32 v1, -v1, v102, v101
	v_div_fmas_f32 v1, v1, v99, v102
	v_div_fixup_f32 v88, v1, v100, v88
	v_pk_mul_f32 v[84:85], v[84:85], v[88:89]
	v_lshlrev_b32_e32 v88, 16, v70
	v_lshlrev_b32_e32 v89, 16, v71
	v_and_b32_e32 v100, 0xffff0000, v70
	v_and_b32_e32 v101, 0xffff0000, v71
	v_pk_fma_f32 v[88:89], v[36:37], v[88:89], v[108:109]
	v_pk_fma_f32 v[90:91], v[38:39], v[100:101], v[90:91]
	v_pk_add_f32 v[88:89], v[52:53], v[88:89]
	v_pk_add_f32 v[90:91], v[54:55], v[90:91]
	v_mul_f32_e32 v1, 0xbfb8aa3b, v88
	v_exp_f32_e32 v108, v1
	v_mul_f32_e32 v1, 0xbfb8aa3b, v90
	v_exp_f32_e32 v100, v1
	v_mul_f32_e32 v1, 0xbfb8aa3b, v89
	v_lshlrev_b32_e32 v102, 16, v86
	v_lshlrev_b32_e32 v103, 16, v87
	v_exp_f32_e32 v109, v1
	v_and_b32_e32 v86, 0xffff0000, v86
	v_and_b32_e32 v87, 0xffff0000, v87
	v_pk_mul_f32 v[102:103], v[12:13], v[102:103]
	v_and_b32_e32 v106, 0xffff0000, v82
	v_and_b32_e32 v107, 0xffff0000, v83
	v_pk_fma_f32 v[102:103], v[28:29], v[104:105], v[102:103]
	v_lshlrev_b32_e32 v105, 16, v75
	v_lshlrev_b32_e32 v104, 16, v74
	v_pk_mul_f32 v[86:87], v[14:15], v[86:87]
	v_pk_fma_f32 v[102:103], v[44:45], v[104:105], v[102:103]
	v_pk_fma_f32 v[86:87], v[30:31], v[106:107], v[86:87]
	v_and_b32_e32 v105, 0xffff0000, v75
	v_and_b32_e32 v104, 0xffff0000, v74
	v_pk_fma_f32 v[86:87], v[46:47], v[104:105], v[86:87]
	v_pk_add_f32 v[104:105], v[108:109], 1.0 op_sel_hi:[1,0]
	v_pk_add_f32 v[102:103], v[60:61], v[102:103]
	v_div_scale_f32 v1, s[20:21], v105, v105, v89
	v_rcp_f32_e32 v99, v1
	v_pk_add_f32 v[86:87], v[62:63], v[86:87]
	s_add_u32 s42, s42, 0x2c00
	s_addc_u32 s43, s43, 0
	v_fma_f32 v101, -v1, v99, 1.0
	v_fmac_f32_e32 v99, v101, v99
	v_div_scale_f32 v101, vcc, v89, v105, v89
	v_mul_f32_e32 v106, v101, v99
	v_fma_f32 v107, -v1, v106, v101
	v_fmac_f32_e32 v106, v107, v99
	v_fma_f32 v1, -v1, v106, v101
	v_div_fmas_f32 v1, v1, v99, v106
	v_div_fixup_f32 v89, v1, v105, v89
	v_div_scale_f32 v1, s[20:21], v104, v104, v88
	v_rcp_f32_e32 v99, v1
	s_cmp_eq_u32 s42, 0x58000
	v_fma_f32 v101, -v1, v99, 1.0
	v_fmac_f32_e32 v99, v101, v99
	v_div_scale_f32 v101, vcc, v88, v104, v88
	v_mul_f32_e32 v105, v101, v99
	v_fma_f32 v106, -v1, v105, v101
	v_fmac_f32_e32 v105, v106, v99
	v_fma_f32 v1, -v1, v105, v101
	v_div_fmas_f32 v1, v1, v99, v105
	v_div_fixup_f32 v88, v1, v104, v88
	v_mul_f32_e32 v1, 0xbfb8aa3b, v91
	v_exp_f32_e32 v101, v1
	v_pk_mul_f32 v[88:89], v[102:103], v[88:89]
	v_pk_add_f32 v[100:101], v[100:101], 1.0 op_sel_hi:[1,0]
	s_nop 0
	v_div_scale_f32 v1, s[20:21], v101, v101, v91
	v_rcp_f32_e32 v99, v1
	s_nop 0
	v_fma_f32 v102, -v1, v99, 1.0
	v_fmac_f32_e32 v99, v102, v99
	v_div_scale_f32 v102, vcc, v91, v101, v91
	v_mul_f32_e32 v103, v102, v99
	v_fma_f32 v104, -v1, v103, v102
	v_fmac_f32_e32 v103, v104, v99
	v_fma_f32 v1, -v1, v103, v102
	v_div_fmas_f32 v1, v1, v99, v103
	v_div_fixup_f32 v91, v1, v101, v91
	v_div_scale_f32 v1, s[20:21], v100, v100, v90
	v_rcp_f32_e32 v99, v1
	s_mov_b64 s[20:21], 0x1600
	v_fma_f32 v101, -v1, v99, 1.0
	v_fmac_f32_e32 v99, v101, v99
	v_div_scale_f32 v101, vcc, v90, v100, v90
	v_mul_f32_e32 v102, v101, v99
	v_fma_f32 v103, -v1, v102, v101
	v_fmac_f32_e32 v102, v103, v99
	v_fma_f32 v1, -v1, v102, v101
	v_div_fmas_f32 v1, v1, v99, v102
	v_div_fixup_f32 v90, v1, v100, v90
	v_pk_mul_f32 v[86:87], v[86:87], v[90:91]
	v_bfe_u32 v91, v85, 16, 1
	v_bfe_u32 v1, v87, 16, 1
	v_bfe_u32 v90, v86, 16, 1
	v_bfe_u32 v99, v84, 16, 1
	v_add3_u32 v84, v84, v99, s18
	v_add3_u32 v85, v85, v91, s18
	v_add3_u32 v86, v86, v90, s18
	v_add3_u32 v1, v87, v1, s18
	v_bfe_u32 v87, v2, 16, 1
	v_bfe_u32 v90, v3, 16, 1
	v_bfe_u32 v91, v88, 16, 1
	v_bfe_u32 v99, v89, 16, 1
	v_add3_u32 v89, v89, v99, s18
	v_add3_u32 v88, v88, v91, s18
	v_add3_u32 v3, v3, v90, s18
	v_add3_u32 v2, v2, v87, s18
	v_lshrrev_b32_e32 v2, 16, v2
	v_lshrrev_b32_e32 v3, 16, v3
	v_lshrrev_b32_e32 v88, 16, v88
	v_lshrrev_b32_e32 v87, 16, v89
	v_and_or_b32 v87, v1, s17, v87
	v_and_or_b32 v86, v86, s17, v88
	v_and_or_b32 v85, v85, s17, v3
	v_and_or_b32 v84, v84, s17, v2
	global_store_dwordx4 v[94:95], v[84:87], off
	v_mov_b64_e32 v[90:91], v[78:79]
	v_lshl_add_u64 v[94:95], v[94:95], 0, s[20:21]
	v_mov_b64_e32 v[86:87], v[82:83]
	v_mov_b64_e32 v[84:85], v[80:81]
	v_mov_b64_e32 v[88:89], v[76:77]
	s_cbranch_scc1 .LBB0_1245
.LBB0_1250:
	v_mov_b64_e32 v[78:79], v[70:71]
	v_mov_b64_e32 v[82:83], v[74:75]
	s_cmp_lg_u32 s42, 0x55400
	v_mov_b32_e32 v2, v0
	v_mov_b32_e32 v3, v0
	v_mov_b64_e32 v[76:77], v[68:69]
	v_mov_b64_e32 v[80:81], v[72:73]
	s_cselect_b64 s[20:21], -1, 0
	v_mov_b32_e32 v1, v0
	v_mov_b64_e32 v[70:71], v[2:3]
	v_mov_b64_e32 v[74:75], v[2:3]
	s_or_b64 s[20:21], s[44:45], s[20:21]
	v_mov_b64_e32 v[68:69], v[0:1]
	v_mov_b64_e32 v[72:73], v[0:1]
	s_and_saveexec_b64 s[46:47], s[20:21]
	s_cbranch_execz .LBB0_1249
	s_waitcnt vmcnt(1)
	v_mov_b64_e32 v[68:69], v[114:115]
	v_mov_b64_e32 v[70:71], v[116:117]
	v_mov_b64_e32 v[72:73], v[118:119]
	v_mov_b64_e32 v[74:75], v[120:121]
	s_cmp_lg_u32 s42, 0x52800
	s_cselect_b64 vcc, -1, 0
	s_or_b64 vcc, s[44:45], vcc
	s_cmp_lg_u32 s42, 0x55400
	s_cselect_b64 s[20:21], -1, 0
	s_and_b64 vcc, vcc, s[20:21]
	s_and_b64 exec, exec, vcc
	s_cbranch_execz .LBB0_1249
	v_lshl_add_u64 v[2:3], v[96:97], 0, s[42:43]
	v_add_co_u32_e32 v122, vcc, 0x6d54c00, v2
	s_nop 1
	v_addc_co_u32_e32 v123, vcc, 0, v3, vcc
	v_add_co_u32_e32 v2, vcc, 0x6d56c00, v2
	s_nop 1
	v_addc_co_u32_e32 v3, vcc, 0, v3, vcc
	global_load_dwordx4 v[114:117], v[122:123], off offset:3072 nt
	global_load_dwordx4 v[118:121], v[2:3], off offset:512 nt
	s_branch .LBB0_1249

.LBB0_2357:
	s_or_b64 exec, exec, s[36:37]
	v_add_co_u32_e32 v2, vcc, s30, v68
	v_and_b32_e32 v1, 0xffffefe0, v79
	s_nop 0
	v_addc_co_u32_e32 v3, vcc, 0, v69, vcc
	v_add_co_u32_e32 v122, vcc, 0x2c00, v68
	s_nop 1
	v_addc_co_u32_e32 v123, vcc, 0, v69, vcc
	v_add_co_u32_e32 v124, vcc, 0x2c00, v2
	s_nop 1
	v_addc_co_u32_e32 v125, vcc, 0, v3, vcc
	global_load_dwordx4 v[68:71], v[68:69], off nt
	s_nop 0
	global_load_dwordx4 v[72:75], v[2:3], off offset:1536 nt
	global_load_dwordx4 v[114:117], v[122:123], off nt
	global_load_dwordx4 v[118:121], v[124:125], off offset:1536 nt
	v_mad_i64_i32 v[2:3], s[36:37], v78, s26, 0
	s_waitcnt vmcnt(0)
	v_mov_b32_e32 v79, v6
	v_mov_b32_e32 v6, v10
	v_lshlrev_b64 v[76:77], 1, v[76:77]
	v_mov_b32_e32 v80, v14
	v_mov_b32_e32 v14, v18
	v_mov_b32_e32 v81, v22
	v_mov_b32_e32 v22, v26
	v_mov_b32_e32 v82, v30
	v_mov_b32_e32 v30, v34
	v_mov_b32_e32 v83, v38
	v_mov_b32_e32 v38, v42
	v_mov_b32_e32 v94, v46
	v_mov_b32_e32 v46, v50
	v_mov_b32_e32 v95, v54
	v_mov_b32_e32 v54, v58
	v_mov_b32_e32 v96, v62
	v_mov_b32_e32 v62, v66
	v_cmp_eq_u32_e32 vcc, s27, v1
	v_mov_b32_e32 v10, v9
	v_mov_b32_e32 v9, v6
	v_mov_b32_e32 v6, v5
	v_mov_b32_e32 v5, v79
	v_mad_i64_i32 v[78:79], s[36:37], v78, s31, v[76:77]
	v_lshl_add_u64 v[2:3], v[2:3], 0, v[76:77]
	v_swap_b32 v66, v65
	v_mov_b32_e32 v34, v33
	v_mov_b32_e32 v18, v17
	v_mov_b32_e32 v50, v49
	v_swap_b32 v58, v57
	v_mov_b32_e32 v26, v25
	v_mov_b32_e32 v42, v41
	v_mov_b32_e32 v33, v30
	v_mov_b32_e32 v17, v14
	v_mov_b32_e32 v49, v46
	v_mov_b32_e32 v25, v22
	v_mov_b32_e32 v41, v38
	v_mov_b32_e32 v62, v61
	v_mov_b32_e32 v30, v29
	v_mov_b32_e32 v14, v13
	v_mov_b32_e32 v46, v45
	v_mov_b32_e32 v54, v53
	v_mov_b32_e32 v22, v21
	v_mov_b32_e32 v38, v37
	v_mov_b32_e32 v61, v96
	v_mov_b32_e32 v29, v82
	v_mov_b32_e32 v13, v80
	v_mov_b32_e32 v45, v94
	v_mov_b32_e32 v53, v95
	v_mov_b32_e32 v21, v81
	v_mov_b32_e32 v37, v83
	v_lshl_add_u64 v[94:95], s[52:53], 0, v[78:79]
	v_lshl_add_u64 v[96:97], s[74:75], 0, v[2:3]
	s_mov_b64 s[36:37], 0
	s_xor_b64 s[38:39], vcc, -1
	s_branch .LBB0_2359
.LBB0_2358:
	s_or_b64 exec, exec, s[40:41]
	v_lshlrev_b32_e32 v109, 16, v89
	v_lshlrev_b32_e32 v108, 16, v88
	v_lshlrev_b32_e32 v111, 16, v77
	v_lshlrev_b32_e32 v110, 16, v76
	v_and_b32_e32 v89, 0xffff0000, v89
	v_and_b32_e32 v88, 0xffff0000, v88
	v_pk_mul_f32 v[108:109], v[8:9], v[108:109]
	s_nop 0
	v_lshlrev_b32_e32 v2, 16, v68
	v_lshlrev_b32_e32 v3, 16, v69
	v_and_b32_e32 v113, 0xffff0000, v77
	v_and_b32_e32 v112, 0xffff0000, v76
	v_pk_fma_f32 v[108:109], v[24:25], v[110:111], v[108:109]
	v_pk_mul_f32 v[88:89], v[10:11], v[88:89]
	v_and_b32_e32 v100, 0xffff0000, v68
	v_and_b32_e32 v101, 0xffff0000, v69
	v_pk_fma_f32 v[2:3], v[40:41], v[2:3], v[108:109]
	v_pk_fma_f32 v[88:89], v[26:27], v[112:113], v[88:89]
	v_pk_add_f32 v[2:3], v[56:57], v[2:3]
	v_pk_fma_f32 v[88:89], v[42:43], v[100:101], v[88:89]
	v_mul_f32_e32 v1, 0xbfb8aa3b, v2
	v_pk_add_f32 v[88:89], v[58:59], v[88:89]
	v_exp_f32_e32 v108, v1
	v_mul_f32_e32 v1, 0xbfb8aa3b, v88
	v_exp_f32_e32 v100, v1
	v_mul_f32_e32 v1, 0xbfb8aa3b, v3
	v_exp_f32_e32 v109, v1
	v_lshlrev_b32_e32 v102, 16, v84
	v_and_b32_e32 v84, 0xffff0000, v84
	v_lshlrev_b32_e32 v103, 16, v85
	v_and_b32_e32 v85, 0xffff0000, v85
	v_and_b32_e32 v106, 0xffff0000, v80
	v_and_b32_e32 v107, 0xffff0000, v81
	v_pk_mul_f32 v[84:85], v[18:19], v[84:85]
	v_lshlrev_b32_e32 v104, 16, v80
	v_pk_fma_f32 v[84:85], v[34:35], v[106:107], v[84:85]
	v_pk_add_f32 v[106:107], v[108:109], 1.0 op_sel_hi:[1,0]
	v_lshlrev_b32_e32 v105, 16, v81
	v_div_scale_f32 v1, s[40:41], v107, v107, v3
	v_rcp_f32_e32 v99, v1
	v_pk_mul_f32 v[102:103], v[16:17], v[102:103]
	v_lshlrev_b32_e32 v109, 16, v91
	v_pk_fma_f32 v[102:103], v[32:33], v[104:105], v[102:103]
	s_nop 0
	v_lshlrev_b32_e32 v105, 16, v73
	v_lshlrev_b32_e32 v104, 16, v72
	v_fma_f32 v101, -v1, v99, 1.0
	v_pk_fma_f32 v[102:103], v[48:49], v[104:105], v[102:103]
	v_and_b32_e32 v105, 0xffff0000, v73
	v_and_b32_e32 v104, 0xffff0000, v72
	v_fmac_f32_e32 v99, v101, v99
	v_div_scale_f32 v101, vcc, v3, v107, v3
	v_pk_fma_f32 v[84:85], v[50:51], v[104:105], v[84:85]
	v_mul_f32_e32 v104, v101, v99
	v_fma_f32 v105, -v1, v104, v101
	v_fmac_f32_e32 v104, v105, v99
	v_div_scale_f32 v105, s[40:41], v106, v106, v2
	v_rcp_f32_e32 v108, v105
	v_fma_f32 v1, -v1, v104, v101
	v_mul_f32_e32 v101, 0xbfb8aa3b, v89
	v_div_fmas_f32 v1, v1, v99, v104
	v_exp_f32_e32 v101, v101
	v_div_fixup_f32 v3, v1, v107, v3
	v_fma_f32 v1, -v105, v108, 1.0
	v_fmac_f32_e32 v108, v1, v108
	v_div_scale_f32 v1, vcc, v2, v106, v2
	v_mul_f32_e32 v99, v1, v108
	v_fma_f32 v104, -v105, v99, v1
	v_pk_add_f32 v[100:101], v[100:101], 1.0 op_sel_hi:[1,0]
	v_fmac_f32_e32 v99, v104, v108
	v_div_scale_f32 v104, s[40:41], v101, v101, v89
	v_fma_f32 v1, -v105, v99, v1
	v_rcp_f32_e32 v105, v104
	v_div_fmas_f32 v1, v1, v108, v99
	v_div_fixup_f32 v2, v1, v106, v2
	v_pk_add_f32 v[102:103], v[64:65], v[102:103]
	v_fma_f32 v1, -v104, v105, 1.0
	v_fmac_f32_e32 v105, v1, v105
	v_div_scale_f32 v1, vcc, v89, v101, v89
	v_mul_f32_e32 v99, v1, v105
	v_pk_mul_f32 v[2:3], v[102:103], v[2:3]
	v_fma_f32 v102, -v104, v99, v1
	v_fmac_f32_e32 v99, v102, v105
	v_div_scale_f32 v102, s[40:41], v100, v100, v88
	v_rcp_f32_e32 v103, v102
	v_fma_f32 v1, -v104, v99, v1
	v_div_fmas_f32 v1, v1, v105, v99
	v_div_fixup_f32 v89, v1, v101, v89
	v_fma_f32 v1, -v102, v103, 1.0
	v_fmac_f32_e32 v103, v1, v103
	v_div_scale_f32 v1, vcc, v88, v100, v88
	v_mul_f32_e32 v99, v1, v103
	v_fma_f32 v101, -v102, v99, v1
	v_fmac_f32_e32 v99, v101, v103
	v_fma_f32 v1, -v102, v99, v1
	v_div_fmas_f32 v1, v1, v103, v99
	v_lshlrev_b32_e32 v108, 16, v90
	v_pk_add_f32 v[84:85], v[66:67], v[84:85]
	v_div_fixup_f32 v88, v1, v100, v88
	v_lshlrev_b32_e32 v111, 16, v79
	v_lshlrev_b32_e32 v110, 16, v78
	v_and_b32_e32 v91, 0xffff0000, v91
	v_and_b32_e32 v90, 0xffff0000, v90
	v_pk_mul_f32 v[108:109], v[4:5], v[108:109]
	v_pk_mul_f32 v[84:85], v[84:85], v[88:89]
	v_lshlrev_b32_e32 v88, 16, v70
	v_lshlrev_b32_e32 v89, 16, v71
	v_and_b32_e32 v113, 0xffff0000, v79
	v_and_b32_e32 v112, 0xffff0000, v78
	v_pk_fma_f32 v[108:109], v[20:21], v[110:111], v[108:109]
	v_pk_mul_f32 v[90:91], v[6:7], v[90:91]
	v_and_b32_e32 v100, 0xffff0000, v70
	v_and_b32_e32 v101, 0xffff0000, v71
	v_pk_fma_f32 v[88:89], v[36:37], v[88:89], v[108:109]
	v_pk_fma_f32 v[90:91], v[22:23], v[112:113], v[90:91]
	v_pk_add_f32 v[88:89], v[52:53], v[88:89]
	v_pk_fma_f32 v[90:91], v[38:39], v[100:101], v[90:91]
	v_mul_f32_e32 v1, 0xbfb8aa3b, v88
	v_pk_add_f32 v[90:91], v[54:55], v[90:91]
	v_exp_f32_e32 v108, v1
	v_mul_f32_e32 v1, 0xbfb8aa3b, v90
	v_exp_f32_e32 v100, v1
	v_mul_f32_e32 v1, 0xbfb8aa3b, v89
	v_exp_f32_e32 v109, v1
	v_lshlrev_b32_e32 v102, 16, v86
	v_and_b32_e32 v86, 0xffff0000, v86
	v_lshlrev_b32_e32 v103, 16, v87
	v_and_b32_e32 v87, 0xffff0000, v87
	v_and_b32_e32 v106, 0xffff0000, v82
	v_and_b32_e32 v107, 0xffff0000, v83
	v_pk_mul_f32 v[86:87], v[14:15], v[86:87]
	v_lshlrev_b32_e32 v104, 16, v82
	v_pk_fma_f32 v[86:87], v[30:31], v[106:107], v[86:87]
	v_pk_add_f32 v[106:107], v[108:109], 1.0 op_sel_hi:[1,0]
	v_lshlrev_b32_e32 v105, 16, v83
	v_div_scale_f32 v1, s[40:41], v107, v107, v89
	v_rcp_f32_e32 v99, v1
	v_pk_mul_f32 v[102:103], v[12:13], v[102:103]
	s_add_u32 s36, s36, 0x2c00
	v_pk_fma_f32 v[102:103], v[28:29], v[104:105], v[102:103]
	v_lshlrev_b32_e32 v105, 16, v75
	v_lshlrev_b32_e32 v104, 16, v74
	v_fma_f32 v101, -v1, v99, 1.0
	v_pk_fma_f32 v[102:103], v[44:45], v[104:105], v[102:103]
	v_and_b32_e32 v105, 0xffff0000, v75
	v_and_b32_e32 v104, 0xffff0000, v74
	v_fmac_f32_e32 v99, v101, v99
	v_div_scale_f32 v101, vcc, v89, v107, v89
	v_pk_fma_f32 v[86:87], v[46:47], v[104:105], v[86:87]
	v_mul_f32_e32 v104, v101, v99
	v_fma_f32 v105, -v1, v104, v101
	v_fmac_f32_e32 v104, v105, v99
	v_div_scale_f32 v105, s[40:41], v106, v106, v88
	v_rcp_f32_e32 v108, v105
	v_fma_f32 v1, -v1, v104, v101
	v_mul_f32_e32 v101, 0xbfb8aa3b, v91
	v_div_fmas_f32 v1, v1, v99, v104
	v_exp_f32_e32 v101, v101
	v_div_fixup_f32 v89, v1, v107, v89
	v_fma_f32 v1, -v105, v108, 1.0
	v_fmac_f32_e32 v108, v1, v108
	v_div_scale_f32 v1, vcc, v88, v106, v88
	v_mul_f32_e32 v99, v1, v108
	v_fma_f32 v104, -v105, v99, v1
	v_pk_add_f32 v[100:101], v[100:101], 1.0 op_sel_hi:[1,0]
	v_fmac_f32_e32 v99, v104, v108
	v_div_scale_f32 v104, s[40:41], v101, v101, v91
	v_fma_f32 v1, -v105, v99, v1
	v_rcp_f32_e32 v105, v104
	v_div_fmas_f32 v1, v1, v108, v99
	v_div_fixup_f32 v88, v1, v106, v88
	v_pk_add_f32 v[102:103], v[60:61], v[102:103]
	v_fma_f32 v1, -v104, v105, 1.0
	v_fmac_f32_e32 v105, v1, v105
	v_div_scale_f32 v1, vcc, v91, v101, v91
	v_mul_f32_e32 v99, v1, v105
	v_pk_mul_f32 v[88:89], v[102:103], v[88:89]
	v_fma_f32 v102, -v104, v99, v1
	v_fmac_f32_e32 v99, v102, v105
	v_div_scale_f32 v102, s[40:41], v100, v100, v90
	v_rcp_f32_e32 v103, v102
	v_fma_f32 v1, -v104, v99, v1
	v_div_fmas_f32 v1, v1, v105, v99
	v_div_fixup_f32 v91, v1, v101, v91
	v_fma_f32 v1, -v102, v103, 1.0
	v_fmac_f32_e32 v103, v1, v103
	v_div_scale_f32 v1, vcc, v90, v100, v90
	v_mul_f32_e32 v99, v1, v103
	v_fma_f32 v101, -v102, v99, v1
	v_fmac_f32_e32 v99, v101, v103
	v_fma_f32 v1, -v102, v99, v1
	v_div_fmas_f32 v1, v1, v103, v99
	v_pk_add_f32 v[86:87], v[62:63], v[86:87]
	v_div_fixup_f32 v90, v1, v100, v90
	v_pk_mul_f32 v[86:87], v[86:87], v[90:91]
	v_bfe_u32 v91, v85, 16, 1
	v_bfe_u32 v1, v87, 16, 1
	v_bfe_u32 v90, v86, 16, 1
	v_bfe_u32 v99, v84, 16, 1
	v_add3_u32 v84, v84, v99, s42
	v_add3_u32 v85, v85, v91, s42
	v_add3_u32 v86, v86, v90, s42
	v_add3_u32 v1, v87, v1, s42
	v_bfe_u32 v87, v2, 16, 1
	v_bfe_u32 v90, v3, 16, 1
	v_bfe_u32 v91, v88, 16, 1
	v_bfe_u32 v99, v89, 16, 1
	v_add3_u32 v89, v89, v99, s42
	v_add3_u32 v88, v88, v91, s42
	v_add3_u32 v3, v3, v90, s42
	v_add3_u32 v2, v2, v87, s42
	v_lshrrev_b32_e32 v2, 16, v2
	v_lshrrev_b32_e32 v3, 16, v3
	v_lshrrev_b32_e32 v88, 16, v88
	v_lshrrev_b32_e32 v87, 16, v89
	v_and_or_b32 v87, v1, s33, v87
	v_and_or_b32 v86, v86, s33, v88
	v_and_or_b32 v85, v85, s33, v3
	v_and_or_b32 v84, v84, s33, v2
	global_store_dwordx4 v[94:95], v[84:87], off
	s_addc_u32 s37, s37, 0
	v_mov_b64_e32 v[90:91], v[78:79]
	v_mov_b64_e32 v[86:87], v[82:83]
	v_lshl_add_u64 v[94:95], v[94:95], 0, s[34:35]
	s_cmp_eq_u32 s36, 0x58000
	v_mov_b64_e32 v[84:85], v[80:81]
	v_mov_b64_e32 v[88:89], v[76:77]
	s_cbranch_scc1 .LBB0_2354
.LBB0_2359:
	v_mov_b64_e32 v[78:79], v[70:71]
	v_mov_b64_e32 v[82:83], v[74:75]
	s_cmp_lg_u32 s36, 0x55400
	v_mov_b32_e32 v2, v0
	v_mov_b32_e32 v3, v0
	v_mov_b64_e32 v[76:77], v[68:69]
	v_mov_b64_e32 v[80:81], v[72:73]
	s_cselect_b64 s[40:41], -1, 0
	v_mov_b32_e32 v1, v0
	v_mov_b64_e32 v[70:71], v[2:3]
	v_mov_b64_e32 v[74:75], v[2:3]
	s_or_b64 s[44:45], s[38:39], s[40:41]
	v_mov_b64_e32 v[68:69], v[0:1]
	v_mov_b64_e32 v[72:73], v[0:1]
	s_and_saveexec_b64 s[40:41], s[44:45]
	s_cbranch_execz .LBB0_2358
	s_waitcnt vmcnt(1)
	v_mov_b64_e32 v[68:69], v[114:115]
	v_mov_b64_e32 v[70:71], v[116:117]
	v_mov_b64_e32 v[72:73], v[118:119]
	v_mov_b64_e32 v[74:75], v[120:121]
	s_cmp_lg_u32 s36, 0x52800
	s_cselect_b64 vcc, -1, 0
	s_or_b64 vcc, s[38:39], vcc
	s_cmp_lg_u32 s36, 0x55400
	s_cselect_b64 s[44:45], -1, 0
	s_and_b64 vcc, vcc, s[44:45]
	s_and_b64 exec, exec, vcc
	s_cbranch_execz .LBB0_2358
	v_lshl_add_u64 v[2:3], v[96:97], 0, s[36:37]
	v_add_co_u32_e32 v122, vcc, 0x6d54c00, v2
	s_nop 1
	v_addc_co_u32_e32 v123, vcc, 0, v3, vcc
	v_add_co_u32_e32 v2, vcc, 0x6d56c00, v2
	s_nop 1
	v_addc_co_u32_e32 v3, vcc, 0, v3, vcc
	global_load_dwordx4 v[114:117], v[122:123], off offset:3072 nt
	global_load_dwordx4 v[118:121], v[2:3], off offset:512 nt
	s_branch .LBB0_2358

.LBB0_2493:
	s_or_b64 exec, exec, s[34:35]
	v_add_co_u32_e32 v2, vcc, s41, v68
	v_and_b32_e32 v1, 0xffffefe0, v79
	s_nop 0
	v_addc_co_u32_e32 v3, vcc, 0, v69, vcc
	v_add_co_u32_e32 v122, vcc, 0x2c00, v68
	s_nop 1
	v_addc_co_u32_e32 v123, vcc, 0, v69, vcc
	v_add_co_u32_e32 v124, vcc, 0x2c00, v2
	s_nop 1
	v_addc_co_u32_e32 v125, vcc, 0, v3, vcc
	global_load_dwordx4 v[68:71], v[68:69], off nt
	s_nop 0
	global_load_dwordx4 v[72:75], v[2:3], off offset:1536 nt
	global_load_dwordx4 v[114:117], v[122:123], off nt
	global_load_dwordx4 v[118:121], v[124:125], off offset:1536 nt
	v_mad_i64_i32 v[2:3], s[34:35], v78, s33, 0
	s_waitcnt vmcnt(0)
	v_mov_b32_e32 v79, v6
	v_mov_b32_e32 v6, v10
	v_lshlrev_b64 v[76:77], 1, v[76:77]
	v_mov_b32_e32 v80, v14
	v_mov_b32_e32 v14, v18
	v_mov_b32_e32 v81, v22
	v_mov_b32_e32 v22, v26
	v_mov_b32_e32 v82, v30
	v_mov_b32_e32 v30, v34
	v_mov_b32_e32 v83, v38
	v_mov_b32_e32 v38, v42
	v_mov_b32_e32 v94, v46
	v_mov_b32_e32 v46, v50
	v_mov_b32_e32 v95, v54
	v_mov_b32_e32 v54, v58
	v_mov_b32_e32 v96, v62
	v_mov_b32_e32 v62, v66
	v_cmp_eq_u32_e32 vcc, s40, v1
	v_mov_b32_e32 v10, v9
	v_mov_b32_e32 v9, v6
	v_mov_b32_e32 v6, v5
	v_mov_b32_e32 v5, v79
	v_mad_i64_i32 v[78:79], s[34:35], v78, s42, v[76:77]
	v_lshl_add_u64 v[2:3], v[2:3], 0, v[76:77]
	v_swap_b32 v66, v65
	v_mov_b32_e32 v34, v33
	v_mov_b32_e32 v18, v17
	v_mov_b32_e32 v50, v49
	v_swap_b32 v58, v57
	v_mov_b32_e32 v26, v25
	v_mov_b32_e32 v42, v41
	v_mov_b32_e32 v33, v30
	v_mov_b32_e32 v17, v14
	v_mov_b32_e32 v49, v46
	v_mov_b32_e32 v25, v22
	v_mov_b32_e32 v41, v38
	v_mov_b32_e32 v62, v61
	v_mov_b32_e32 v30, v29
	v_mov_b32_e32 v14, v13
	v_mov_b32_e32 v46, v45
	v_mov_b32_e32 v54, v53
	v_mov_b32_e32 v22, v21
	v_mov_b32_e32 v38, v37
	v_mov_b32_e32 v61, v96
	v_mov_b32_e32 v29, v82
	v_mov_b32_e32 v13, v80
	v_mov_b32_e32 v45, v94
	v_mov_b32_e32 v53, v95
	v_mov_b32_e32 v21, v81
	v_mov_b32_e32 v37, v83
	v_lshl_add_u64 v[94:95], s[24:25], 0, v[78:79]
	v_lshl_add_u64 v[96:97], s[74:75], 0, v[2:3]
	s_mov_b64 s[34:35], 0
	s_xor_b64 s[36:37], vcc, -1
	s_branch .LBB0_2495
.LBB0_2494:
	s_or_b64 exec, exec, s[38:39]
	v_lshlrev_b32_e32 v109, 16, v89
	v_lshlrev_b32_e32 v108, 16, v88
	v_lshlrev_b32_e32 v111, 16, v77
	v_lshlrev_b32_e32 v110, 16, v76
	v_and_b32_e32 v89, 0xffff0000, v89
	v_and_b32_e32 v88, 0xffff0000, v88
	v_pk_mul_f32 v[108:109], v[8:9], v[108:109]
	s_nop 0
	v_lshlrev_b32_e32 v2, 16, v68
	v_lshlrev_b32_e32 v3, 16, v69
	v_and_b32_e32 v113, 0xffff0000, v77
	v_and_b32_e32 v112, 0xffff0000, v76
	v_pk_fma_f32 v[108:109], v[24:25], v[110:111], v[108:109]
	v_pk_mul_f32 v[88:89], v[10:11], v[88:89]
	v_and_b32_e32 v100, 0xffff0000, v68
	v_and_b32_e32 v101, 0xffff0000, v69
	v_pk_fma_f32 v[2:3], v[40:41], v[2:3], v[108:109]
	v_pk_fma_f32 v[88:89], v[26:27], v[112:113], v[88:89]
	v_pk_add_f32 v[2:3], v[56:57], v[2:3]
	v_pk_fma_f32 v[88:89], v[42:43], v[100:101], v[88:89]
	v_mul_f32_e32 v1, 0xbfb8aa3b, v2
	v_pk_add_f32 v[88:89], v[58:59], v[88:89]
	v_exp_f32_e32 v108, v1
	v_mul_f32_e32 v1, 0xbfb8aa3b, v88
	v_exp_f32_e32 v100, v1
	v_mul_f32_e32 v1, 0xbfb8aa3b, v3
	v_exp_f32_e32 v109, v1
	v_lshlrev_b32_e32 v102, 16, v84
	v_and_b32_e32 v84, 0xffff0000, v84
	v_lshlrev_b32_e32 v103, 16, v85
	v_and_b32_e32 v85, 0xffff0000, v85
	v_and_b32_e32 v106, 0xffff0000, v80
	v_and_b32_e32 v107, 0xffff0000, v81
	v_pk_mul_f32 v[84:85], v[18:19], v[84:85]
	v_lshlrev_b32_e32 v104, 16, v80
	v_pk_fma_f32 v[84:85], v[34:35], v[106:107], v[84:85]
	v_pk_add_f32 v[106:107], v[108:109], 1.0 op_sel_hi:[1,0]
	v_lshlrev_b32_e32 v105, 16, v81
	v_div_scale_f32 v1, s[38:39], v107, v107, v3
	v_rcp_f32_e32 v99, v1
	v_pk_mul_f32 v[102:103], v[16:17], v[102:103]
	v_lshlrev_b32_e32 v109, 16, v91
	v_pk_fma_f32 v[102:103], v[32:33], v[104:105], v[102:103]
	s_nop 0
	v_lshlrev_b32_e32 v105, 16, v73
	v_lshlrev_b32_e32 v104, 16, v72
	v_fma_f32 v101, -v1, v99, 1.0
	v_pk_fma_f32 v[102:103], v[48:49], v[104:105], v[102:103]
	v_and_b32_e32 v105, 0xffff0000, v73
	v_and_b32_e32 v104, 0xffff0000, v72
	v_fmac_f32_e32 v99, v101, v99
	v_div_scale_f32 v101, vcc, v3, v107, v3
	v_pk_fma_f32 v[84:85], v[50:51], v[104:105], v[84:85]
	v_mul_f32_e32 v104, v101, v99
	v_fma_f32 v105, -v1, v104, v101
	v_fmac_f32_e32 v104, v105, v99
	v_div_scale_f32 v105, s[38:39], v106, v106, v2
	v_rcp_f32_e32 v108, v105
	v_fma_f32 v1, -v1, v104, v101
	v_mul_f32_e32 v101, 0xbfb8aa3b, v89
	v_div_fmas_f32 v1, v1, v99, v104
	v_exp_f32_e32 v101, v101
	v_div_fixup_f32 v3, v1, v107, v3
	v_fma_f32 v1, -v105, v108, 1.0
	v_fmac_f32_e32 v108, v1, v108
	v_div_scale_f32 v1, vcc, v2, v106, v2
	v_mul_f32_e32 v99, v1, v108
	v_fma_f32 v104, -v105, v99, v1
	v_pk_add_f32 v[100:101], v[100:101], 1.0 op_sel_hi:[1,0]
	v_fmac_f32_e32 v99, v104, v108
	v_div_scale_f32 v104, s[38:39], v101, v101, v89
	v_fma_f32 v1, -v105, v99, v1
	v_rcp_f32_e32 v105, v104
	v_div_fmas_f32 v1, v1, v108, v99
	v_div_fixup_f32 v2, v1, v106, v2
	v_pk_add_f32 v[102:103], v[64:65], v[102:103]
	v_fma_f32 v1, -v104, v105, 1.0
	v_fmac_f32_e32 v105, v1, v105
	v_div_scale_f32 v1, vcc, v89, v101, v89
	v_mul_f32_e32 v99, v1, v105
	v_pk_mul_f32 v[2:3], v[102:103], v[2:3]
	v_fma_f32 v102, -v104, v99, v1
	v_fmac_f32_e32 v99, v102, v105
	v_div_scale_f32 v102, s[38:39], v100, v100, v88
	v_rcp_f32_e32 v103, v102
	v_fma_f32 v1, -v104, v99, v1
	v_div_fmas_f32 v1, v1, v105, v99
	v_div_fixup_f32 v89, v1, v101, v89
	v_fma_f32 v1, -v102, v103, 1.0
	v_fmac_f32_e32 v103, v1, v103
	v_div_scale_f32 v1, vcc, v88, v100, v88
	v_mul_f32_e32 v99, v1, v103
	v_fma_f32 v101, -v102, v99, v1
	v_fmac_f32_e32 v99, v101, v103
	v_fma_f32 v1, -v102, v99, v1
	v_div_fmas_f32 v1, v1, v103, v99
	v_lshlrev_b32_e32 v108, 16, v90
	v_pk_add_f32 v[84:85], v[66:67], v[84:85]
	v_div_fixup_f32 v88, v1, v100, v88
	v_lshlrev_b32_e32 v111, 16, v79
	v_lshlrev_b32_e32 v110, 16, v78
	v_and_b32_e32 v91, 0xffff0000, v91
	v_and_b32_e32 v90, 0xffff0000, v90
	v_pk_mul_f32 v[108:109], v[4:5], v[108:109]
	v_pk_mul_f32 v[84:85], v[84:85], v[88:89]
	v_lshlrev_b32_e32 v88, 16, v70
	v_lshlrev_b32_e32 v89, 16, v71
	v_and_b32_e32 v113, 0xffff0000, v79
	v_and_b32_e32 v112, 0xffff0000, v78
	v_pk_fma_f32 v[108:109], v[20:21], v[110:111], v[108:109]
	v_pk_mul_f32 v[90:91], v[6:7], v[90:91]
	v_and_b32_e32 v100, 0xffff0000, v70
	v_and_b32_e32 v101, 0xffff0000, v71
	v_pk_fma_f32 v[88:89], v[36:37], v[88:89], v[108:109]
	v_pk_fma_f32 v[90:91], v[22:23], v[112:113], v[90:91]
	v_pk_add_f32 v[88:89], v[52:53], v[88:89]
	v_pk_fma_f32 v[90:91], v[38:39], v[100:101], v[90:91]
	v_mul_f32_e32 v1, 0xbfb8aa3b, v88
	v_pk_add_f32 v[90:91], v[54:55], v[90:91]
	v_exp_f32_e32 v108, v1
	v_mul_f32_e32 v1, 0xbfb8aa3b, v90
	v_exp_f32_e32 v100, v1
	v_mul_f32_e32 v1, 0xbfb8aa3b, v89
	v_exp_f32_e32 v109, v1
	v_lshlrev_b32_e32 v102, 16, v86
	v_and_b32_e32 v86, 0xffff0000, v86
	v_lshlrev_b32_e32 v103, 16, v87
	v_and_b32_e32 v87, 0xffff0000, v87
	v_and_b32_e32 v106, 0xffff0000, v82
	v_and_b32_e32 v107, 0xffff0000, v83
	v_pk_mul_f32 v[86:87], v[14:15], v[86:87]
	v_lshlrev_b32_e32 v104, 16, v82
	v_pk_fma_f32 v[86:87], v[30:31], v[106:107], v[86:87]
	v_pk_add_f32 v[106:107], v[108:109], 1.0 op_sel_hi:[1,0]
	v_lshlrev_b32_e32 v105, 16, v83
	v_div_scale_f32 v1, s[38:39], v107, v107, v89
	v_rcp_f32_e32 v99, v1
	v_pk_mul_f32 v[102:103], v[12:13], v[102:103]
	s_add_u32 s34, s34, 0x2c00
	v_pk_fma_f32 v[102:103], v[28:29], v[104:105], v[102:103]
	v_lshlrev_b32_e32 v105, 16, v75
	v_lshlrev_b32_e32 v104, 16, v74
	v_fma_f32 v101, -v1, v99, 1.0
	v_pk_fma_f32 v[102:103], v[44:45], v[104:105], v[102:103]
	v_and_b32_e32 v105, 0xffff0000, v75
	v_and_b32_e32 v104, 0xffff0000, v74
	v_fmac_f32_e32 v99, v101, v99
	v_div_scale_f32 v101, vcc, v89, v107, v89
	v_pk_fma_f32 v[86:87], v[46:47], v[104:105], v[86:87]
	v_mul_f32_e32 v104, v101, v99
	v_fma_f32 v105, -v1, v104, v101
	v_fmac_f32_e32 v104, v105, v99
	v_div_scale_f32 v105, s[38:39], v106, v106, v88
	v_rcp_f32_e32 v108, v105
	v_fma_f32 v1, -v1, v104, v101
	v_mul_f32_e32 v101, 0xbfb8aa3b, v91
	v_div_fmas_f32 v1, v1, v99, v104
	v_exp_f32_e32 v101, v101
	v_div_fixup_f32 v89, v1, v107, v89
	v_fma_f32 v1, -v105, v108, 1.0
	v_fmac_f32_e32 v108, v1, v108
	v_div_scale_f32 v1, vcc, v88, v106, v88
	v_mul_f32_e32 v99, v1, v108
	v_fma_f32 v104, -v105, v99, v1
	v_pk_add_f32 v[100:101], v[100:101], 1.0 op_sel_hi:[1,0]
	v_fmac_f32_e32 v99, v104, v108
	v_div_scale_f32 v104, s[38:39], v101, v101, v91
	v_fma_f32 v1, -v105, v99, v1
	v_rcp_f32_e32 v105, v104
	v_div_fmas_f32 v1, v1, v108, v99
	v_div_fixup_f32 v88, v1, v106, v88
	v_pk_add_f32 v[102:103], v[60:61], v[102:103]
	v_fma_f32 v1, -v104, v105, 1.0
	v_fmac_f32_e32 v105, v1, v105
	v_div_scale_f32 v1, vcc, v91, v101, v91
	v_mul_f32_e32 v99, v1, v105
	v_pk_mul_f32 v[88:89], v[102:103], v[88:89]
	v_fma_f32 v102, -v104, v99, v1
	v_fmac_f32_e32 v99, v102, v105
	v_div_scale_f32 v102, s[38:39], v100, v100, v90
	v_rcp_f32_e32 v103, v102
	v_fma_f32 v1, -v104, v99, v1
	v_div_fmas_f32 v1, v1, v105, v99
	v_div_fixup_f32 v91, v1, v101, v91
	v_fma_f32 v1, -v102, v103, 1.0
	v_fmac_f32_e32 v103, v1, v103
	v_div_scale_f32 v1, vcc, v90, v100, v90
	v_mul_f32_e32 v99, v1, v103
	v_fma_f32 v101, -v102, v99, v1
	v_fmac_f32_e32 v99, v101, v103
	v_fma_f32 v1, -v102, v99, v1
	v_div_fmas_f32 v1, v1, v103, v99
	v_pk_add_f32 v[86:87], v[62:63], v[86:87]
	v_div_fixup_f32 v90, v1, v100, v90
	v_pk_mul_f32 v[86:87], v[86:87], v[90:91]
	v_bfe_u32 v91, v85, 16, 1
	v_bfe_u32 v1, v87, 16, 1
	v_bfe_u32 v90, v86, 16, 1
	v_bfe_u32 v99, v84, 16, 1
	v_add3_u32 v84, v84, v99, s44
	v_add3_u32 v85, v85, v91, s44
	v_add3_u32 v86, v86, v90, s44
	v_add3_u32 v1, v87, v1, s44
	v_bfe_u32 v87, v2, 16, 1
	v_bfe_u32 v90, v3, 16, 1
	v_bfe_u32 v91, v88, 16, 1
	v_bfe_u32 v99, v89, 16, 1
	v_add3_u32 v89, v89, v99, s44
	v_add3_u32 v88, v88, v91, s44
	v_add3_u32 v3, v3, v90, s44
	v_add3_u32 v2, v2, v87, s44
	v_lshrrev_b32_e32 v2, 16, v2
	v_lshrrev_b32_e32 v3, 16, v3
	v_lshrrev_b32_e32 v88, 16, v88
	v_lshrrev_b32_e32 v87, 16, v89
	v_and_or_b32 v87, v1, s43, v87
	v_and_or_b32 v86, v86, s43, v88
	v_and_or_b32 v85, v85, s43, v3
	v_and_or_b32 v84, v84, s43, v2
	global_store_dwordx4 v[94:95], v[84:87], off
	s_addc_u32 s35, s35, 0
	v_mov_b64_e32 v[90:91], v[78:79]
	v_mov_b64_e32 v[86:87], v[82:83]
	v_lshl_add_u64 v[94:95], v[94:95], 0, s[28:29]
	s_cmp_eq_u32 s34, 0x58000
	v_mov_b64_e32 v[84:85], v[80:81]
	v_mov_b64_e32 v[88:89], v[76:77]
	s_cbranch_scc1 .LBB0_2490
.LBB0_2495:
	v_mov_b64_e32 v[78:79], v[70:71]
	v_mov_b64_e32 v[82:83], v[74:75]
	s_cmp_lg_u32 s34, 0x55400
	v_mov_b32_e32 v2, v0
	v_mov_b32_e32 v3, v0
	v_mov_b64_e32 v[76:77], v[68:69]
	v_mov_b64_e32 v[80:81], v[72:73]
	s_cselect_b64 s[38:39], -1, 0
	v_mov_b32_e32 v1, v0
	v_mov_b64_e32 v[70:71], v[2:3]
	v_mov_b64_e32 v[74:75], v[2:3]
	s_or_b64 s[46:47], s[36:37], s[38:39]
	v_mov_b64_e32 v[68:69], v[0:1]
	v_mov_b64_e32 v[72:73], v[0:1]
	s_and_saveexec_b64 s[38:39], s[46:47]
	s_cbranch_execz .LBB0_2494
	s_waitcnt vmcnt(1)
	v_mov_b64_e32 v[68:69], v[114:115]
	v_mov_b64_e32 v[70:71], v[116:117]
	v_mov_b64_e32 v[72:73], v[118:119]
	v_mov_b64_e32 v[74:75], v[120:121]
	s_cmp_lg_u32 s34, 0x52800
	s_cselect_b64 vcc, -1, 0
	s_or_b64 vcc, s[36:37], vcc
	s_cmp_lg_u32 s34, 0x55400
	s_cselect_b64 s[46:47], -1, 0
	s_and_b64 vcc, vcc, s[46:47]
	s_and_b64 exec, exec, vcc
	s_cbranch_execz .LBB0_2494
	v_lshl_add_u64 v[2:3], v[96:97], 0, s[34:35]
	v_add_co_u32_e32 v122, vcc, 0x6d54c00, v2
	s_nop 1
	v_addc_co_u32_e32 v123, vcc, 0, v3, vcc
	v_add_co_u32_e32 v2, vcc, 0x6d56c00, v2
	s_nop 1
	v_addc_co_u32_e32 v3, vcc, 0, v3, vcc
	global_load_dwordx4 v[114:117], v[122:123], off offset:3072 nt
	global_load_dwordx4 v[118:121], v[2:3], off offset:512 nt
	s_branch .LBB0_2494
